# replace cooperative-groups grid.sync with a flat agent-scope counter barrier; + LRU scan1 init hoist
# speedup vs baseline: 1.0564x; 1.0564x over previous
; __global__ void __launch_bounds__(NTHR, 2) mk_fwd(Args args) {
;     ...
;     grid.sync();
.LBB0_379:
	v_lshrrev_b32_e32 v1, 20, v0
	v_lshrrev_b32_e32 v0, 10, v0
	v_or_b32_e32 v0, v0, v1
	s_movk_i32 s2, 0x3ff
	v_and_or_b32 v0, v0, s2, v246
	v_cmp_eq_u32_e32 vcc, 0, v0
	s_waitcnt lgkmcnt(0)
	s_barrier
	s_and_saveexec_b64 s[2:3], vcc
	s_cbranch_execz .LBB0_389
	buffer_wbl2 sc1
	s_waitcnt vmcnt(0)
	s_add_u32 s4, s38, 0x8000
	s_addc_u32 s5, s39, 0
	v_mov_b32_e32 v0, 0
	v_mov_b32_e32 v1, 1
	global_atomic_add v0, v1, s[4:5]
.Lgs_spin:
	global_load_dword v2, v0, s[4:5] sc1
	s_waitcnt vmcnt(0)
	v_readfirstlane_b32 s6, v2
	s_nop 0
	s_cmp_ge_u32 s6, s78
	s_cbranch_scc1 .Lgs_done
	s_sleep 1
	s_branch .Lgs_spin
.Lgs_done:
	buffer_inv sc1
	s_waitcnt vmcnt(0)
